# P4 gate GEMM K-loop hand-scheduled too (3-slot B-fragment ring, skewed tail, K-chunk rotation)
# speedup vs baseline: 1.0051x; 1.0051x over previous
; __device__ __forceinline__ void gemm_gate3(f32x4 (&g)[3][2][4], const bf16_t* __restrict__ A, const bf16_t* __restrict__ Bt0, int nk, unsigned char* lds, int tid) {
;     ...
;     for (int kt = 0; kt < nk; ++kt) {
;         if (!late && kt + 1 < nk) issue(kt + 1, (kt + 1) & 1);
;         const unsigned char* As = lds + (kt & 1) * STAGE;
;         const unsigned char* Bs = As + 128 * 128;
; #pragma unroll
;         for (int ks = 0; ks < 2; ++ks) {
;             if (ks == 1 && late && kt + 1 < nk) issue(kt + 1, (kt + 1) & 1);
;             const int co = ((ks * 4 + fq) ^ sz) * 16;
;             bf16x8 af[2];
; #pragma unroll
;             for (int m = 0; m < 2; ++m) af[m] = *(const bf16x8*)(As + (wr * 32 + m * 16 + fr) * 128 + co);
; #pragma unroll
;             for (int i = 0; i < 3; ++i) {
;                 bf16x8 bfr[4];
; #pragma unroll
;                 for (int n = 0; n < 4; ++n) bfr[n] = *(const bf16x8*)(Bs + (i * 128 + wc * 64 + n * 16 + fr) * 128 + co);
; #pragma unroll
;                 for (int m = 0; m < 2; ++m)
; #pragma unroll
;                     for (int n = 0; n < 4; ++n) g[i][m][n] = __builtin_amdgcn_mfma_f32_16x16x32_bf16(bfr[n], af[m], g[i][m][n], 0, 0, 0);
;                 if (i < 2) __builtin_amdgcn_sched_barrier(0);
;             }
;         }
;         asm volatile("s_waitcnt vmcnt(0) lgkmcnt(0)" ::: "memory");
;         __builtin_amdgcn_s_barrier();
;         asm volatile("" ::: "memory");
;     }
.LBB0_687:
	s_mov_b32 s75, 0
	v_readlane_b32 s76, v253, 0
	s_lshr_b32 s50, s76, 3
	s_and_b32 s50, s50, 15
	s_lshl_b32 s50, s50, 7
	s_cmpk_eq_i32 s50, 0x780
	s_cselect_b32 s50, 0, s50
	s_mov_b32 s51, 0
	s_mov_b32 s47, 0
	s_lshl_b32 s54, s75, 16
	s_xor_b32 s70, s54, 0x10000
	s_add_i32 s70, s7, s70
	v_add3_u32 v155, s54, v129, v103
	v_add3_u32 v154, s54, v129, v101
	v_add3_u32 v157, s54, v130, v103
	v_add3_u32 v156, s54, v130, v101
	ds_read_b128 v[190:193], v154
	ds_read_b128 v[194:197], v154 offset:2048
	ds_read_b128 v[138:141], v155 offset:16384
	ds_read_b128 v[142:145], v155 offset:18432
	ds_read_b128 v[146:149], v155 offset:20480
	ds_read_b128 v[150:153], v155 offset:22528
	ds_read_b128 v[214:217], v155 offset:32768
	ds_read_b128 v[218:221], v155 offset:34816
	ds_read_b128 v[222:225], v155 offset:36864
	ds_read_b128 v[226:229], v155 offset:38912
	v_lshl_add_u64 v[246:247], v[122:123], 0, s[50:51]
	v_lshl_add_u64 v[248:249], v[120:121], 0, s[50:51]
	v_lshl_add_u64 v[250:251], v[246:247], 0, s[94:95]
	s_mov_b32 m0, s70
	s_nop 0
	global_load_lds_dwordx4 v[250:251], off
	v_lshl_add_u64 v[206:207], v[246:247], 0, s[14:15]
	s_add_i32 m0, s70, 0x2000
	s_nop 0
	global_load_lds_dwordx4 v[206:207], off
	ds_read_b128 v[230:233], v155 offset:49152
	ds_read_b128 v[234:237], v155 offset:51200
	ds_read_b128 v[238:241], v155 offset:53248
	s_waitcnt lgkmcnt(12)
	ds_read_b128 v[242:245], v155 offset:55296
	s_waitcnt lgkmcnt(12)
	ds_read_b128 v[198:201], v156
	s_waitcnt lgkmcnt(12)
	ds_read_b128 v[202:205], v156 offset:2048
	s_waitcnt lgkmcnt(10)
	v_mfma_f32_16x16x32_bf16 v[92:95], v[138:141], v[190:193], v[92:95]
	v_mfma_f32_16x16x32_bf16 v[88:91], v[142:145], v[190:193], v[88:91]
	v_mfma_f32_16x16x32_bf16 v[84:87], v[146:149], v[190:193], v[84:87]
	v_mfma_f32_16x16x32_bf16 v[80:83], v[150:153], v[190:193], v[80:83]
	v_mfma_f32_16x16x32_bf16 v[76:79], v[138:141], v[194:197], v[76:79]
	v_mfma_f32_16x16x32_bf16 v[72:75], v[142:145], v[194:197], v[72:75]
	v_mfma_f32_16x16x32_bf16 v[68:71], v[146:149], v[194:197], v[68:71]
	v_mfma_f32_16x16x32_bf16 v[64:67], v[150:153], v[194:197], v[64:67]
	ds_read_b128 v[138:141], v157 offset:16384
	ds_read_b128 v[142:145], v157 offset:18432
	ds_read_b128 v[146:149], v157 offset:20480
	s_waitcnt lgkmcnt(12)
	ds_read_b128 v[150:153], v157 offset:22528
	v_lshl_add_u64 v[250:251], v[248:249], 0, s[16:17]
	s_add_i32 m0, s70, 0x4000
	s_nop 0
	global_load_lds_dwordx4 v[250:251], off
	v_lshl_add_u64 v[206:207], v[248:249], 0, s[24:25]
	s_add_i32 m0, s70, 0x6000
	s_nop 0
	global_load_lds_dwordx4 v[206:207], off
	s_waitcnt lgkmcnt(10)
	v_mfma_f32_16x16x32_bf16 v[60:63], v[214:217], v[190:193], v[60:63]
	v_mfma_f32_16x16x32_bf16 v[52:55], v[218:221], v[190:193], v[52:55]
	v_mfma_f32_16x16x32_bf16 v[48:51], v[222:225], v[190:193], v[48:51]
	v_mfma_f32_16x16x32_bf16 v[44:47], v[226:229], v[190:193], v[44:47]
	v_mfma_f32_16x16x32_bf16 v[40:43], v[214:217], v[194:197], v[40:43]
	v_mfma_f32_16x16x32_bf16 v[36:39], v[218:221], v[194:197], v[36:39]
	v_mfma_f32_16x16x32_bf16 v[32:35], v[222:225], v[194:197], v[32:35]
	v_mfma_f32_16x16x32_bf16 v[28:31], v[226:229], v[194:197], v[28:31]
	ds_read_b128 v[214:217], v157 offset:32768
	ds_read_b128 v[218:221], v157 offset:34816
	ds_read_b128 v[222:225], v157 offset:36864
	s_waitcnt lgkmcnt(12)
	ds_read_b128 v[226:229], v157 offset:38912
	s_mov_b64 s[56:57], 0x202080
	v_lshl_add_u64 v[250:251], v[248:249], 0, s[56:57]
	s_add_i32 m0, s70, 0x8000
	s_nop 0
	global_load_lds_dwordx4 v[250:251], off
	s_mov_b64 s[56:57], 0x222080
	v_lshl_add_u64 v[206:207], v[248:249], 0, s[56:57]
	s_add_i32 m0, s70, 0xa000
	s_nop 0
	global_load_lds_dwordx4 v[206:207], off
	s_waitcnt lgkmcnt(10)
	v_mfma_f32_16x16x32_bf16 v[24:27], v[230:233], v[190:193], v[24:27]
	v_mfma_f32_16x16x32_bf16 v[20:23], v[234:237], v[190:193], v[20:23]
	v_mfma_f32_16x16x32_bf16 v[16:19], v[238:241], v[190:193], v[16:19]
	v_mfma_f32_16x16x32_bf16 v[12:15], v[242:245], v[190:193], v[12:15]
	v_mfma_f32_16x16x32_bf16 v[8:11], v[230:233], v[194:197], v[8:11]
	v_mfma_f32_16x16x32_bf16 v[4:7], v[234:237], v[194:197], v[4:7]
	v_mfma_f32_16x16x32_bf16 v[0:3], v[238:241], v[194:197], v[0:3]
	v_mfma_f32_16x16x32_bf16 v[56:59], v[242:245], v[194:197], v[56:59]
	ds_read_b128 v[230:233], v157 offset:49152
	ds_read_b128 v[234:237], v157 offset:51200
	ds_read_b128 v[238:241], v157 offset:53248
	s_waitcnt lgkmcnt(12)
	ds_read_b128 v[242:245], v157 offset:55296
	s_mov_b64 s[56:57], 0x402080
	v_lshl_add_u64 v[250:251], v[248:249], 0, s[56:57]
	s_add_i32 m0, s70, 0xc000
	s_nop 0
	global_load_lds_dwordx4 v[250:251], off
	s_mov_b64 s[56:57], 0x422080
	v_lshl_add_u64 v[206:207], v[248:249], 0, s[56:57]
	s_add_i32 m0, s70, 0xe000
	s_nop 0
	global_load_lds_dwordx4 v[206:207], off
	s_waitcnt lgkmcnt(8)
	v_mfma_f32_16x16x32_bf16 v[92:95], v[138:141], v[198:201], v[92:95]
	v_mfma_f32_16x16x32_bf16 v[88:91], v[142:145], v[198:201], v[88:91]
	v_mfma_f32_16x16x32_bf16 v[84:87], v[146:149], v[198:201], v[84:87]
	v_mfma_f32_16x16x32_bf16 v[80:83], v[150:153], v[198:201], v[80:83]
	v_mfma_f32_16x16x32_bf16 v[76:79], v[138:141], v[202:205], v[76:79]
	v_mfma_f32_16x16x32_bf16 v[72:75], v[142:145], v[202:205], v[72:75]
	v_mfma_f32_16x16x32_bf16 v[68:71], v[146:149], v[202:205], v[68:71]
	v_mfma_f32_16x16x32_bf16 v[64:67], v[150:153], v[202:205], v[64:67]
	s_waitcnt lgkmcnt(4)
	v_mfma_f32_16x16x32_bf16 v[60:63], v[214:217], v[198:201], v[60:63]
	v_mfma_f32_16x16x32_bf16 v[52:55], v[218:221], v[198:201], v[52:55]
	v_mfma_f32_16x16x32_bf16 v[48:51], v[222:225], v[198:201], v[48:51]
	v_mfma_f32_16x16x32_bf16 v[44:47], v[226:229], v[198:201], v[44:47]
	v_mfma_f32_16x16x32_bf16 v[40:43], v[214:217], v[202:205], v[40:43]
	v_mfma_f32_16x16x32_bf16 v[36:39], v[218:221], v[202:205], v[36:39]
	v_mfma_f32_16x16x32_bf16 v[32:35], v[222:225], v[202:205], v[32:35]
	v_mfma_f32_16x16x32_bf16 v[28:31], v[226:229], v[202:205], v[28:31]
	s_add_u32 s50, s50, 0x80
	s_cmpk_eq_i32 s50, 0x780
	s_cselect_b32 s50, 0, s50
	s_add_i32 s47, s47, 1
	s_xor_b32 s75, s75, 1
	s_waitcnt vmcnt(0) lgkmcnt(0)
	s_barrier
; __device__ __forceinline__ void gemm_gate3(f32x4 (&g)[3][2][4], const bf16_t* __restrict__ A, const bf16_t* __restrict__ Bt0, int nk, unsigned char* lds, int tid) {
;     ...
;     for (int kt = 0; kt < nk; ++kt) {
;         if (!late && kt + 1 < nk) issue(kt + 1, (kt + 1) & 1);
;         const unsigned char* As = lds + (kt & 1) * STAGE;
;         const unsigned char* Bs = As + 128 * 128;
; #pragma unroll
;         for (int ks = 0; ks < 2; ++ks) {
;             if (ks == 1 && late && kt + 1 < nk) issue(kt + 1, (kt + 1) & 1);
;             const int co = ((ks * 4 + fq) ^ sz) * 16;
;             bf16x8 af[2];
; #pragma unroll
;             for (int m = 0; m < 2; ++m) af[m] = *(const bf16x8*)(As + (wr * 32 + m * 16 + fr) * 128 + co);
; #pragma unroll
;             for (int i = 0; i < 3; ++i) {
;                 bf16x8 bfr[4];
; #pragma unroll
;                 for (int n = 0; n < 4; ++n) bfr[n] = *(const bf16x8*)(Bs + (i * 128 + wc * 64 + n * 16 + fr) * 128 + co);
; #pragma unroll
;                 for (int m = 0; m < 2; ++m)
; #pragma unroll
;                     for (int n = 0; n < 4; ++n) g[i][m][n] = __builtin_amdgcn_mfma_f32_16x16x32_bf16(bfr[n], af[m], g[i][m][n], 0, 0, 0);
;                 if (i < 2) __builtin_amdgcn_sched_barrier(0);
;             }
;         }
;         asm volatile("s_waitcnt vmcnt(0) lgkmcnt(0)" ::: "memory");
;         __builtin_amdgcn_s_barrier();
;         asm volatile("" ::: "memory");
;     }
.Lp4_gloop:
	s_lshl_b32 s54, s75, 16
	s_xor_b32 s70, s54, 0x10000
	s_add_i32 s70, s7, s70
	v_add3_u32 v155, s54, v129, v103
	v_add3_u32 v154, s54, v129, v101
	v_add3_u32 v157, s54, v130, v103
	v_add3_u32 v156, s54, v130, v101
	ds_read_b128 v[190:193], v154
	ds_read_b128 v[194:197], v154 offset:2048
	ds_read_b128 v[138:141], v155 offset:16384
	ds_read_b128 v[142:145], v155 offset:18432
	ds_read_b128 v[146:149], v155 offset:20480
	ds_read_b128 v[150:153], v155 offset:22528
	ds_read_b128 v[214:217], v155 offset:32768
	ds_read_b128 v[218:221], v155 offset:34816
	ds_read_b128 v[222:225], v155 offset:36864
	ds_read_b128 v[226:229], v155 offset:38912
	v_lshl_add_u64 v[246:247], v[122:123], 0, s[50:51]
	v_lshl_add_u64 v[248:249], v[120:121], 0, s[50:51]
	v_mfma_f32_16x16x32_bf16 v[24:27], v[230:233], v[198:201], v[24:27]
	v_mfma_f32_16x16x32_bf16 v[20:23], v[234:237], v[198:201], v[20:23]
	v_mfma_f32_16x16x32_bf16 v[16:19], v[238:241], v[198:201], v[16:19]
	v_mfma_f32_16x16x32_bf16 v[12:15], v[242:245], v[198:201], v[12:15]
	v_mfma_f32_16x16x32_bf16 v[8:11], v[230:233], v[202:205], v[8:11]
	v_mfma_f32_16x16x32_bf16 v[4:7], v[234:237], v[202:205], v[4:7]
	v_mfma_f32_16x16x32_bf16 v[0:3], v[238:241], v[202:205], v[0:3]
	v_mfma_f32_16x16x32_bf16 v[56:59], v[242:245], v[202:205], v[56:59]
	v_lshl_add_u64 v[250:251], v[246:247], 0, s[94:95]
	s_mov_b32 m0, s70
	s_nop 0
	global_load_lds_dwordx4 v[250:251], off
	v_lshl_add_u64 v[206:207], v[246:247], 0, s[14:15]
	s_add_i32 m0, s70, 0x2000
	s_nop 0
	global_load_lds_dwordx4 v[206:207], off
	s_waitcnt lgkmcnt(0)
	ds_read_b128 v[230:233], v155 offset:49152
	ds_read_b128 v[234:237], v155 offset:51200
	ds_read_b128 v[238:241], v155 offset:53248
	ds_read_b128 v[242:245], v155 offset:55296
	ds_read_b128 v[198:201], v156
	ds_read_b128 v[202:205], v156 offset:2048
	v_mfma_f32_16x16x32_bf16 v[92:95], v[138:141], v[190:193], v[92:95]
	v_mfma_f32_16x16x32_bf16 v[88:91], v[142:145], v[190:193], v[88:91]
	v_mfma_f32_16x16x32_bf16 v[84:87], v[146:149], v[190:193], v[84:87]
	v_mfma_f32_16x16x32_bf16 v[80:83], v[150:153], v[190:193], v[80:83]
	v_mfma_f32_16x16x32_bf16 v[76:79], v[138:141], v[194:197], v[76:79]
	v_mfma_f32_16x16x32_bf16 v[72:75], v[142:145], v[194:197], v[72:75]
	v_mfma_f32_16x16x32_bf16 v[68:71], v[146:149], v[194:197], v[68:71]
	v_mfma_f32_16x16x32_bf16 v[64:67], v[150:153], v[194:197], v[64:67]
	ds_read_b128 v[138:141], v157 offset:16384
	ds_read_b128 v[142:145], v157 offset:18432
	ds_read_b128 v[146:149], v157 offset:20480
	ds_read_b128 v[150:153], v157 offset:22528
	v_lshl_add_u64 v[250:251], v[248:249], 0, s[16:17]
	s_add_i32 m0, s70, 0x4000
	s_nop 0
	global_load_lds_dwordx4 v[250:251], off
	v_lshl_add_u64 v[206:207], v[248:249], 0, s[24:25]
	s_add_i32 m0, s70, 0x6000
	s_nop 0
	global_load_lds_dwordx4 v[206:207], off
	v_mfma_f32_16x16x32_bf16 v[60:63], v[214:217], v[190:193], v[60:63]
	v_mfma_f32_16x16x32_bf16 v[52:55], v[218:221], v[190:193], v[52:55]
	v_mfma_f32_16x16x32_bf16 v[48:51], v[222:225], v[190:193], v[48:51]
	v_mfma_f32_16x16x32_bf16 v[44:47], v[226:229], v[190:193], v[44:47]
	v_mfma_f32_16x16x32_bf16 v[40:43], v[214:217], v[194:197], v[40:43]
	v_mfma_f32_16x16x32_bf16 v[36:39], v[218:221], v[194:197], v[36:39]
	v_mfma_f32_16x16x32_bf16 v[32:35], v[222:225], v[194:197], v[32:35]
	v_mfma_f32_16x16x32_bf16 v[28:31], v[226:229], v[194:197], v[28:31]
	ds_read_b128 v[214:217], v157 offset:32768
	ds_read_b128 v[218:221], v157 offset:34816
	ds_read_b128 v[222:225], v157 offset:36864
	s_waitcnt lgkmcnt(12)
	ds_read_b128 v[226:229], v157 offset:38912
	s_mov_b64 s[56:57], 0x202080
	v_lshl_add_u64 v[250:251], v[248:249], 0, s[56:57]
	s_add_i32 m0, s70, 0x8000
	s_nop 0
	global_load_lds_dwordx4 v[250:251], off
	s_mov_b64 s[56:57], 0x222080
	v_lshl_add_u64 v[206:207], v[248:249], 0, s[56:57]
	s_add_i32 m0, s70, 0xa000
	s_nop 0
	global_load_lds_dwordx4 v[206:207], off
	s_waitcnt lgkmcnt(10)
	v_mfma_f32_16x16x32_bf16 v[24:27], v[230:233], v[190:193], v[24:27]
	v_mfma_f32_16x16x32_bf16 v[20:23], v[234:237], v[190:193], v[20:23]
	v_mfma_f32_16x16x32_bf16 v[16:19], v[238:241], v[190:193], v[16:19]
	v_mfma_f32_16x16x32_bf16 v[12:15], v[242:245], v[190:193], v[12:15]
	v_mfma_f32_16x16x32_bf16 v[8:11], v[230:233], v[194:197], v[8:11]
	v_mfma_f32_16x16x32_bf16 v[4:7], v[234:237], v[194:197], v[4:7]
	v_mfma_f32_16x16x32_bf16 v[0:3], v[238:241], v[194:197], v[0:3]
	v_mfma_f32_16x16x32_bf16 v[56:59], v[242:245], v[194:197], v[56:59]
	ds_read_b128 v[230:233], v157 offset:49152
	ds_read_b128 v[234:237], v157 offset:51200
	ds_read_b128 v[238:241], v157 offset:53248
	s_waitcnt lgkmcnt(12)
	ds_read_b128 v[242:245], v157 offset:55296
	s_mov_b64 s[56:57], 0x402080
	v_lshl_add_u64 v[250:251], v[248:249], 0, s[56:57]
	s_add_i32 m0, s70, 0xc000
	s_nop 0
	global_load_lds_dwordx4 v[250:251], off
	s_mov_b64 s[56:57], 0x422080
	v_lshl_add_u64 v[206:207], v[248:249], 0, s[56:57]
	s_add_i32 m0, s70, 0xe000
	s_nop 0
	global_load_lds_dwordx4 v[206:207], off
	s_waitcnt lgkmcnt(8)
	v_mfma_f32_16x16x32_bf16 v[92:95], v[138:141], v[198:201], v[92:95]
	v_mfma_f32_16x16x32_bf16 v[88:91], v[142:145], v[198:201], v[88:91]
	v_mfma_f32_16x16x32_bf16 v[84:87], v[146:149], v[198:201], v[84:87]
	v_mfma_f32_16x16x32_bf16 v[80:83], v[150:153], v[198:201], v[80:83]
	v_mfma_f32_16x16x32_bf16 v[76:79], v[138:141], v[202:205], v[76:79]
	v_mfma_f32_16x16x32_bf16 v[72:75], v[142:145], v[202:205], v[72:75]
	v_mfma_f32_16x16x32_bf16 v[68:71], v[146:149], v[202:205], v[68:71]
	v_mfma_f32_16x16x32_bf16 v[64:67], v[150:153], v[202:205], v[64:67]
	s_waitcnt lgkmcnt(4)
	v_mfma_f32_16x16x32_bf16 v[60:63], v[214:217], v[198:201], v[60:63]
	v_mfma_f32_16x16x32_bf16 v[52:55], v[218:221], v[198:201], v[52:55]
	v_mfma_f32_16x16x32_bf16 v[48:51], v[222:225], v[198:201], v[48:51]
	v_mfma_f32_16x16x32_bf16 v[44:47], v[226:229], v[198:201], v[44:47]
	v_mfma_f32_16x16x32_bf16 v[40:43], v[214:217], v[202:205], v[40:43]
	v_mfma_f32_16x16x32_bf16 v[36:39], v[218:221], v[202:205], v[36:39]
	v_mfma_f32_16x16x32_bf16 v[32:35], v[222:225], v[202:205], v[32:35]
	v_mfma_f32_16x16x32_bf16 v[28:31], v[226:229], v[202:205], v[28:31]
	s_add_u32 s50, s50, 0x80
	s_cmpk_eq_i32 s50, 0x780
	s_cselect_b32 s50, 0, s50
	s_add_i32 s47, s47, 1
	s_xor_b32 s75, s75, 1
	s_waitcnt vmcnt(0) lgkmcnt(0)
	s_barrier
	s_cmpk_lg_i32 s47, 15
	s_cbranch_scc1 .Lp4_gloop
	v_mfma_f32_16x16x32_bf16 v[24:27], v[230:233], v[198:201], v[24:27]
	v_mfma_f32_16x16x32_bf16 v[20:23], v[234:237], v[198:201], v[20:23]
	v_mfma_f32_16x16x32_bf16 v[16:19], v[238:241], v[198:201], v[16:19]
	v_mfma_f32_16x16x32_bf16 v[12:15], v[242:245], v[198:201], v[12:15]
	v_mfma_f32_16x16x32_bf16 v[8:11], v[230:233], v[202:205], v[8:11]
	v_mfma_f32_16x16x32_bf16 v[4:7], v[234:237], v[202:205], v[4:7]
	v_mfma_f32_16x16x32_bf16 v[0:3], v[238:241], v[202:205], v[0:3]
	v_mfma_f32_16x16x32_bf16 v[56:59], v[242:245], v[202:205], v[56:59]
